# in-proj GEMM V-transpose epilogue: eight row sum-of-squares loads issued once up front; the per-group vmcnt(0) drains of the 2-byte stores removed
# baseline (speedup 1.0000x reference)
; DI unsigned pk2(float lo, float hi) { const f32x2_t v = {lo, hi}; return __builtin_bit_cast(unsigned, __builtin_convertvector(v, bf16x2_t)); }
;     DI void operator()(const f32x4 (&acc)[2][2][4][2], const Unit& u, int wr, int wc, int fr, int fq) const {
;     ...
;                 for (int m = 0; m < 4; ++m) { const int row = row0 + ai * HALF + m * 16; const float rs = rsqrtf(ssq[row] * (1.f / 2048.f) + 1e-6f);
;                     const int bb = row >> 12, t = row & 4095;
; #pragma unroll
;                     for (int bj = 0; bj < 2; ++bj) { const int hh = (u.pn - 11) * 2 + bj;
;                         bf16_t* vp = vt + ((size_t)(bb * 6 + hh) * 128 + wc * 32 + 8 * fq) * 4096 + t;
;                         const f32x4 v0 = acc[ai][bj][m][0] * rs, v1 = acc[ai][bj][m][1] * rs;
;                         const unsigned w0 = pk2(v0[0], v0[1]), w1 = pk2(v0[2], v0[3]), w2 = pk2(v1[0], v1[1]), w3 = pk2(v1[2], v1[3]);
;                         vp[0] = (bf16_t)(w0 & 0xffffu); vp[4096] = (bf16_t)(w0 >> 16); vp[2 * 4096] = (bf16_t)(w1 & 0xffffu); vp[3 * 4096] = (bf16_t)(w1 >> 16);
;                         vp[4 * 4096] = (bf16_t)(w2 & 0xffffu); vp[5 * 4096] = (bf16_t)(w2 >> 16); vp[6 * 4096] = (bf16_t)(w3 & 0xffffu); vp[7 * 4096] = (bf16_t)(w3 >> 16); } }
.LBB0_510:
	s_andn2_b64 vcc, exec, s[24:25]
	s_cbranch_vccnz .LBB0_512
	v_ashrrev_i32_e32 v145, 31, v144
	v_lshl_add_u64 v[146:147], v[144:145], 2, s[80:81]
	global_load_dword v145, v[146:147], off
	global_load_dword v168, v[146:147], off offset:64
	global_load_dword v169, v[146:147], off offset:128
	global_load_dword v170, v[146:147], off offset:192
	global_load_dword v171, v[146:147], off offset:512
	global_load_dword v172, v[146:147], off offset:576
	global_load_dword v173, v[146:147], off offset:640
	global_load_dword v174, v[146:147], off offset:704
	s_lshl_b32 s6, s22, 1
	s_sub_i32 s15, s6, 22
	s_ashr_i32 s6, s17, 12
	s_mul_i32 s6, s6, 6
	s_add_i32 s24, s6, s15
	s_ashr_i32 s25, s24, 31
	s_lshl_b64 s[22:23], s[24:25], 20
	s_movk_i32 s17, 0x2000
	s_movk_i32 s26, 0x4000
	s_movk_i32 s27, 0x6000
	s_mov_b32 s28, 0x8000
	s_mov_b32 s29, 0xa000
	s_mov_b32 s30, 0xc000
	s_or_b32 s24, s24, 1
	s_ashr_i32 s25, s24, 31
	s_mov_b32 s7, 0xe000
	s_lshl_b64 s[24:25], s[24:25], 20
	s_movk_i32 s6, 0xfdf
	s_waitcnt vmcnt(0)
	v_fmamk_f32 v145, v145, 0x3a000000, v240
	v_cmp_gt_f32_e32 vcc, s33, v145
	v_mul_f32_e32 v148, 0x4b800000, v145
	s_nop 0
	v_cndmask_b32_e32 v145, v145, v148, vcc
	v_rsq_f32_e32 v145, v145
	s_nop 0
	v_mul_f32_e32 v148, 0x45800000, v145
	v_cndmask_b32_e32 v148, v145, v148, vcc
	v_and_b32_e32 v145, 0xfcf, v144
	v_lshlrev_b32_e32 v204, 1, v145
	v_lshl_add_u64 v[156:157], s[8:9], 0, v[204:205]
	v_lshl_add_u64 v[158:159], v[156:157], 0, s[22:23]
	v_lshl_add_u64 v[158:159], v[158:159], 0, v[136:137]
	v_pk_mul_f32 v[160:161], v[70:71], v[148:149] op_sel_hi:[1,0]
	v_pk_mul_f32 v[162:163], v[68:69], v[148:149] op_sel_hi:[1,0]
	v_cvt_pk_bf16_f32 v150, v160, v161
	v_add_co_u32_e32 v160, vcc, s17, v158
	v_cvt_pk_bf16_f32 v145, v162, v163
	s_nop 0
	v_addc_co_u32_e32 v161, vcc, 0, v159, vcc
	global_store_short_d16_hi v[160:161], v145, off
	v_add_co_u32_e32 v160, vcc, s26, v158
	v_pk_mul_f32 v[166:167], v[56:57], v[148:149] op_sel_hi:[1,0]
	s_nop 0
	v_addc_co_u32_e32 v161, vcc, 0, v159, vcc
	global_store_short v[160:161], v150, off
	v_add_co_u32_e32 v160, vcc, s27, v158
	v_cvt_pk_bf16_f32 v152, v166, v167
	s_nop 0
	v_addc_co_u32_e32 v161, vcc, 0, v159, vcc
	global_store_short_d16_hi v[160:161], v150, off
	v_add_co_u32_e32 v160, vcc, s28, v158
	global_store_short v[158:159], v145, off
	s_nop 0
	v_addc_co_u32_e32 v161, vcc, 0, v159, vcc
	global_store_short v[160:161], v152, off
	v_add_co_u32_e32 v160, vcc, s29, v158
	v_lshl_add_u64 v[156:157], v[156:157], 0, s[24:25]
	s_nop 0
	v_addc_co_u32_e32 v161, vcc, 0, v159, vcc
	global_store_short_d16_hi v[160:161], v152, off
	v_add_co_u32_e32 v160, vcc, s30, v158
	v_lshl_add_u64 v[156:157], v[156:157], 0, v[136:137]
	s_nop 0
	v_addc_co_u32_e32 v161, vcc, 0, v159, vcc
	v_add_co_u32_e32 v158, vcc, s7, v158
	v_pk_mul_f32 v[126:127], v[126:127], v[148:149] op_sel_hi:[1,0]
	s_nop 0
	v_addc_co_u32_e32 v159, vcc, 0, v159, vcc
	v_pk_mul_f32 v[124:125], v[124:125], v[148:149] op_sel_hi:[1,0]
	v_pk_mul_f32 v[120:121], v[120:121], v[148:149] op_sel_hi:[1,0]
	v_cvt_pk_bf16_f32 v124, v124, v125
	v_cvt_pk_bf16_f32 v125, v126, v127
	v_cvt_pk_bf16_f32 v126, v120, v121
	v_add_co_u32_e32 v120, vcc, s17, v156
	v_pk_mul_f32 v[122:123], v[122:123], v[148:149] op_sel_hi:[1,0]
	s_nop 0
	v_addc_co_u32_e32 v121, vcc, 0, v157, vcc
	global_store_short_d16_hi v[120:121], v124, off
	v_add_co_u32_e32 v120, vcc, s26, v156
	v_cvt_pk_bf16_f32 v122, v122, v123
	s_nop 0
	v_addc_co_u32_e32 v121, vcc, 0, v157, vcc
	global_store_short v[120:121], v125, off
	v_add_co_u32_e32 v120, vcc, s27, v156
	global_store_short v[156:157], v124, off
	s_nop 0
	v_addc_co_u32_e32 v121, vcc, 0, v157, vcc
	global_store_short_d16_hi v[120:121], v125, off
	v_add_co_u32_e32 v120, vcc, s28, v156
	v_pk_mul_f32 v[164:165], v[58:59], v[148:149] op_sel_hi:[1,0]
	s_nop 0
	v_addc_co_u32_e32 v121, vcc, 0, v157, vcc
	global_store_short v[120:121], v126, off
	v_add_co_u32_e32 v120, vcc, s29, v156
	v_cvt_pk_bf16_f32 v154, v164, v165
	s_nop 0
	v_addc_co_u32_e32 v121, vcc, 0, v157, vcc
	global_store_short_d16_hi v[120:121], v126, off
	v_add_co_u32_e32 v120, vcc, s30, v156
	global_store_short v[160:161], v154, off
	s_nop 0
	v_addc_co_u32_e32 v121, vcc, 0, v157, vcc
	global_store_short v[120:121], v122, off
	v_add_co_u32_e32 v120, vcc, s7, v156
	global_store_short_d16_hi v[158:159], v154, off
	s_nop 0
	v_addc_co_u32_e32 v121, vcc, 0, v157, vcc
	global_store_short_d16_hi v[120:121], v122, off
	v_or_b32_e32 v120, 16, v144
	v_ashrrev_i32_e32 v121, 31, v120
	v_lshl_add_u64 v[120:121], v[120:121], 2, s[80:81]
	v_mov_b32_e32 v120, v168
	s_nop 0
	v_fmamk_f32 v120, v120, 0x3a000000, v240
	v_cmp_gt_f32_e32 vcc, s33, v120
	v_mul_f32_e32 v121, 0x4b800000, v120
	s_nop 0
	v_cndmask_b32_e32 v120, v120, v121, vcc
	v_rsq_f32_e32 v120, v120
	s_nop 0
	v_mul_f32_e32 v121, 0x45800000, v120
	v_cndmask_b32_e32 v120, v120, v121, vcc
	v_bitop3_b32 v121, v144, s6, 16 bitop3:0xc8
	v_lshlrev_b32_e32 v204, 1, v121
	v_lshl_add_u64 v[122:123], s[8:9], 0, v[204:205]
	v_lshl_add_u64 v[124:125], v[122:123], 0, s[22:23]
	v_lshl_add_u64 v[124:125], v[124:125], 0, v[136:137]
	v_pk_mul_f32 v[126:127], v[54:55], v[120:121] op_sel_hi:[1,0]
	v_pk_mul_f32 v[156:157], v[52:53], v[120:121] op_sel_hi:[1,0]
	v_cvt_pk_bf16_f32 v145, v126, v127
	v_add_co_u32_e32 v126, vcc, s17, v124
	v_pk_mul_f32 v[158:159], v[50:51], v[120:121] op_sel_hi:[1,0]
	v_pk_mul_f32 v[160:161], v[48:49], v[120:121] op_sel_hi:[1,0]
	v_cvt_pk_bf16_f32 v121, v156, v157
	v_addc_co_u32_e32 v127, vcc, 0, v125, vcc
	global_store_short_d16_hi v[126:127], v121, off
	v_add_co_u32_e32 v126, vcc, s26, v124
	v_cvt_pk_bf16_f32 v148, v160, v161
	s_nop 0
; DI unsigned pk2(float lo, float hi) { const f32x2_t v = {lo, hi}; return __builtin_bit_cast(unsigned, __builtin_convertvector(v, bf16x2_t)); }
;     DI void operator()(const f32x4 (&acc)[2][2][4][2], const Unit& u, int wr, int wc, int fr, int fq) const {
;     ...
;                     for (int bj = 0; bj < 2; ++bj) { const int hh = (u.pn - 11) * 2 + bj;
;                         bf16_t* vp = vt + ((size_t)(bb * 6 + hh) * 128 + wc * 32 + 8 * fq) * 4096 + t;
;                         const f32x4 v0 = acc[ai][bj][m][0] * rs, v1 = acc[ai][bj][m][1] * rs;
;                         const unsigned w0 = pk2(v0[0], v0[1]), w1 = pk2(v0[2], v0[3]), w2 = pk2(v1[0], v1[1]), w3 = pk2(v1[2], v1[3]);
;                         vp[0] = (bf16_t)(w0 & 0xffffu); vp[4096] = (bf16_t)(w0 >> 16); vp[2 * 4096] = (bf16_t)(w1 & 0xffffu); vp[3 * 4096] = (bf16_t)(w1 >> 16);
;                         vp[4 * 4096] = (bf16_t)(w2 & 0xffffu); vp[5 * 4096] = (bf16_t)(w2 >> 16); vp[6 * 4096] = (bf16_t)(w3 & 0xffffu); vp[7 * 4096] = (bf16_t)(w3 >> 16); } }
	v_addc_co_u32_e32 v127, vcc, 0, v125, vcc
	global_store_short v[126:127], v145, off
	v_add_co_u32_e32 v126, vcc, s27, v124
	global_store_short v[124:125], v121, off
	s_nop 0
	v_addc_co_u32_e32 v127, vcc, 0, v125, vcc
	global_store_short_d16_hi v[126:127], v145, off
	v_add_co_u32_e32 v126, vcc, s28, v124
	v_lshl_add_u64 v[122:123], v[122:123], 0, s[24:25]
	s_nop 0
	v_addc_co_u32_e32 v127, vcc, 0, v125, vcc
	global_store_short v[126:127], v148, off
	v_add_co_u32_e32 v126, vcc, s29, v124
	v_lshl_add_u64 v[122:123], v[122:123], 0, v[136:137]
	s_nop 0
	v_addc_co_u32_e32 v127, vcc, 0, v125, vcc
	global_store_short_d16_hi v[126:127], v148, off
	v_add_co_u32_e32 v126, vcc, s30, v124
	v_pk_mul_f32 v[118:119], v[118:119], v[120:121] op_sel_hi:[1,0]
	s_nop 0
	v_addc_co_u32_e32 v127, vcc, 0, v125, vcc
	v_add_co_u32_e32 v124, vcc, s7, v124
	v_pk_mul_f32 v[116:117], v[116:117], v[120:121] op_sel_hi:[1,0]
	s_nop 0
	v_addc_co_u32_e32 v125, vcc, 0, v125, vcc
	v_pk_mul_f32 v[112:113], v[112:113], v[120:121] op_sel_hi:[1,0]
	v_cvt_pk_bf16_f32 v116, v116, v117
	v_cvt_pk_bf16_f32 v117, v118, v119
	v_cvt_pk_bf16_f32 v118, v112, v113
	v_add_co_u32_e32 v112, vcc, s17, v122
	v_pk_mul_f32 v[114:115], v[114:115], v[120:121] op_sel_hi:[1,0]
	s_nop 0
	v_addc_co_u32_e32 v113, vcc, 0, v123, vcc
	global_store_short_d16_hi v[112:113], v116, off
	v_add_co_u32_e32 v112, vcc, s26, v122
	v_cvt_pk_bf16_f32 v114, v114, v115
	s_nop 0
	v_addc_co_u32_e32 v113, vcc, 0, v123, vcc
	global_store_short v[112:113], v117, off
	v_add_co_u32_e32 v112, vcc, s27, v122
	s_movk_i32 s6, 0xfef
	s_nop 0
	v_addc_co_u32_e32 v113, vcc, 0, v123, vcc
	global_store_short_d16_hi v[112:113], v117, off
	v_add_co_u32_e32 v112, vcc, s28, v122
	global_store_short v[122:123], v116, off
	s_nop 0
	v_addc_co_u32_e32 v113, vcc, 0, v123, vcc
	global_store_short v[112:113], v118, off
	v_add_co_u32_e32 v112, vcc, s29, v122
	v_cvt_pk_bf16_f32 v150, v158, v159
	s_nop 0
	v_addc_co_u32_e32 v113, vcc, 0, v123, vcc
	global_store_short_d16_hi v[112:113], v118, off
	v_add_co_u32_e32 v112, vcc, s30, v122
	global_store_short_d16_hi v[124:125], v150, off
	s_nop 0
	v_addc_co_u32_e32 v113, vcc, 0, v123, vcc
	global_store_short v[112:113], v114, off
	v_add_co_u32_e32 v112, vcc, s7, v122
	global_store_short v[126:127], v150, off
	s_nop 0
	v_addc_co_u32_e32 v113, vcc, 0, v123, vcc
	global_store_short_d16_hi v[112:113], v114, off
	v_or_b32_e32 v112, 32, v144
	v_ashrrev_i32_e32 v113, 31, v112
	v_lshl_add_u64 v[112:113], v[112:113], 2, s[80:81]
	v_mov_b32_e32 v112, v169
	s_nop 0
	v_fmamk_f32 v112, v112, 0x3a000000, v240
	v_cmp_gt_f32_e32 vcc, s33, v112
	v_mul_f32_e32 v113, 0x4b800000, v112
	s_nop 0
	v_cndmask_b32_e32 v112, v112, v113, vcc
	v_rsq_f32_e32 v112, v112
	s_nop 0
	v_mul_f32_e32 v113, 0x45800000, v112
	v_cndmask_b32_e32 v112, v112, v113, vcc
	v_bitop3_b32 v113, v144, s6, 32 bitop3:0xc8
	v_lshlrev_b32_e32 v204, 1, v113
	v_lshl_add_u64 v[114:115], s[8:9], 0, v[204:205]
	v_lshl_add_u64 v[116:117], v[114:115], 0, s[22:23]
	v_lshl_add_u64 v[116:117], v[116:117], 0, v[136:137]
	v_pk_mul_f32 v[118:119], v[46:47], v[112:113] op_sel_hi:[1,0]
	v_pk_mul_f32 v[120:121], v[44:45], v[112:113] op_sel_hi:[1,0]
	v_pk_mul_f32 v[122:123], v[42:43], v[112:113] op_sel_hi:[1,0]
	v_pk_mul_f32 v[124:125], v[40:41], v[112:113] op_sel_hi:[1,0]
	v_cvt_pk_bf16_f32 v113, v120, v121
	v_cvt_pk_bf16_f32 v120, v118, v119
	v_add_co_u32_e32 v118, vcc, s17, v116
	v_cvt_pk_bf16_f32 v121, v124, v125
	s_nop 0
	v_addc_co_u32_e32 v119, vcc, 0, v117, vcc
	global_store_short_d16_hi v[118:119], v113, off
	v_add_co_u32_e32 v118, vcc, s26, v116
	global_store_short v[116:117], v113, off
	s_nop 0
	v_addc_co_u32_e32 v119, vcc, 0, v117, vcc
	global_store_short v[118:119], v120, off
	v_add_co_u32_e32 v118, vcc, s27, v116
	v_lshl_add_u64 v[114:115], v[114:115], 0, s[24:25]
	s_nop 0
	v_addc_co_u32_e32 v119, vcc, 0, v117, vcc
	global_store_short_d16_hi v[118:119], v120, off
	v_add_co_u32_e32 v118, vcc, s28, v116
	v_lshl_add_u64 v[114:115], v[114:115], 0, v[136:137]
	s_nop 0
	v_addc_co_u32_e32 v119, vcc, 0, v117, vcc
	global_store_short v[118:119], v121, off
	v_add_co_u32_e32 v118, vcc, s29, v116
	v_pk_mul_f32 v[110:111], v[110:111], v[112:113] op_sel_hi:[1,0]
	s_nop 0
	v_addc_co_u32_e32 v119, vcc, 0, v117, vcc
	global_store_short_d16_hi v[118:119], v121, off
	v_add_co_u32_e32 v118, vcc, s30, v116
	v_pk_mul_f32 v[108:109], v[108:109], v[112:113] op_sel_hi:[1,0]
	s_nop 0
	v_addc_co_u32_e32 v119, vcc, 0, v117, vcc
	v_add_co_u32_e32 v116, vcc, s7, v116
	v_pk_mul_f32 v[104:105], v[104:105], v[112:113] op_sel_hi:[1,0]
	s_nop 0
	v_addc_co_u32_e32 v117, vcc, 0, v117, vcc
	v_cvt_pk_bf16_f32 v108, v108, v109
	v_cvt_pk_bf16_f32 v109, v110, v111
	v_cvt_pk_bf16_f32 v110, v104, v105
	v_add_co_u32_e32 v104, vcc, s17, v114
	v_pk_mul_f32 v[106:107], v[106:107], v[112:113] op_sel_hi:[1,0]
	s_nop 0
	v_addc_co_u32_e32 v105, vcc, 0, v115, vcc
	global_store_short_d16_hi v[104:105], v108, off
	v_add_co_u32_e32 v104, vcc, s26, v114
	v_cvt_pk_bf16_f32 v106, v106, v107
	s_nop 0
	v_addc_co_u32_e32 v105, vcc, 0, v115, vcc
	global_store_short v[104:105], v109, off
	v_add_co_u32_e32 v104, vcc, s27, v114
	s_movk_i32 s6, 0xfff
	s_nop 0
	v_addc_co_u32_e32 v105, vcc, 0, v115, vcc
	global_store_short_d16_hi v[104:105], v109, off
	v_add_co_u32_e32 v104, vcc, s28, v114
	global_store_short v[114:115], v108, off
	s_nop 0
	v_addc_co_u32_e32 v105, vcc, 0, v115, vcc
	global_store_short v[104:105], v110, off
	v_add_co_u32_e32 v104, vcc, s29, v114
	v_cvt_pk_bf16_f32 v122, v122, v123
	s_nop 0
	v_addc_co_u32_e32 v105, vcc, 0, v115, vcc
	global_store_short_d16_hi v[104:105], v110, off
	v_add_co_u32_e32 v104, vcc, s30, v114
; DI unsigned pk2(float lo, float hi) { const f32x2_t v = {lo, hi}; return __builtin_bit_cast(unsigned, __builtin_convertvector(v, bf16x2_t)); }
;     DI void operator()(const f32x4 (&acc)[2][2][4][2], const Unit& u, int wr, int wc, int fr, int fq) const {
;     ...
;                 for (int m = 0; m < 4; ++m) { const int row = row0 + ai * HALF + m * 16; const float rs = rsqrtf(ssq[row] * (1.f / 2048.f) + 1e-6f);
;                     const int bb = row >> 12, t = row & 4095;
; #pragma unroll
;                     for (int bj = 0; bj < 2; ++bj) { const int hh = (u.pn - 11) * 2 + bj;
;                         bf16_t* vp = vt + ((size_t)(bb * 6 + hh) * 128 + wc * 32 + 8 * fq) * 4096 + t;
;                         const f32x4 v0 = acc[ai][bj][m][0] * rs, v1 = acc[ai][bj][m][1] * rs;
;                         const unsigned w0 = pk2(v0[0], v0[1]), w1 = pk2(v0[2], v0[3]), w2 = pk2(v1[0], v1[1]), w3 = pk2(v1[2], v1[3]);
;                         vp[0] = (bf16_t)(w0 & 0xffffu); vp[4096] = (bf16_t)(w0 >> 16); vp[2 * 4096] = (bf16_t)(w1 & 0xffffu); vp[3 * 4096] = (bf16_t)(w1 >> 16);
;                         vp[4 * 4096] = (bf16_t)(w2 & 0xffffu); vp[5 * 4096] = (bf16_t)(w2 >> 16); vp[6 * 4096] = (bf16_t)(w3 & 0xffffu); vp[7 * 4096] = (bf16_t)(w3 >> 16); } }
	global_store_short_d16_hi v[116:117], v122, off
	s_nop 0
	v_addc_co_u32_e32 v105, vcc, 0, v115, vcc
	global_store_short v[104:105], v106, off
	v_add_co_u32_e32 v104, vcc, s7, v114
	global_store_short v[118:119], v122, off
	s_nop 0
	v_addc_co_u32_e32 v105, vcc, 0, v115, vcc
	global_store_short_d16_hi v[104:105], v106, off
	v_or_b32_e32 v104, 48, v144
	v_ashrrev_i32_e32 v105, 31, v104
	v_lshl_add_u64 v[104:105], v[104:105], 2, s[80:81]
	v_mov_b32_e32 v104, v170
	s_nop 0
	v_fmamk_f32 v104, v104, 0x3a000000, v240
	v_cmp_gt_f32_e32 vcc, s33, v104
	v_mul_f32_e32 v105, 0x4b800000, v104
	s_nop 0
	v_cndmask_b32_e32 v104, v104, v105, vcc
	v_rsq_f32_e32 v104, v104
	s_nop 0
	v_mul_f32_e32 v105, 0x45800000, v104
	v_cndmask_b32_e32 v104, v104, v105, vcc
	v_bitop3_b32 v105, v144, s6, 48 bitop3:0xc8
	v_lshlrev_b32_e32 v204, 1, v105
	v_lshl_add_u64 v[106:107], s[8:9], 0, v[204:205]
	v_lshl_add_u64 v[108:109], v[106:107], 0, s[22:23]
	v_lshl_add_u64 v[108:109], v[108:109], 0, v[136:137]
	v_pk_mul_f32 v[110:111], v[38:39], v[104:105] op_sel_hi:[1,0]
	v_pk_mul_f32 v[112:113], v[36:37], v[104:105] op_sel_hi:[1,0]
	v_pk_mul_f32 v[114:115], v[34:35], v[104:105] op_sel_hi:[1,0]
	v_pk_mul_f32 v[116:117], v[32:33], v[104:105] op_sel_hi:[1,0]
	v_cvt_pk_bf16_f32 v105, v112, v113
	v_cvt_pk_bf16_f32 v112, v110, v111
	v_add_co_u32_e32 v110, vcc, s17, v108
	v_cvt_pk_bf16_f32 v113, v116, v117
	s_nop 0
	v_addc_co_u32_e32 v111, vcc, 0, v109, vcc
	global_store_short_d16_hi v[110:111], v105, off
	v_add_co_u32_e32 v110, vcc, s26, v108
	global_store_short v[108:109], v105, off
	s_nop 0
	v_addc_co_u32_e32 v111, vcc, 0, v109, vcc
	global_store_short v[110:111], v112, off
	v_add_co_u32_e32 v110, vcc, s27, v108
	v_lshl_add_u64 v[106:107], v[106:107], 0, s[24:25]
	s_nop 0
	v_addc_co_u32_e32 v111, vcc, 0, v109, vcc
	global_store_short_d16_hi v[110:111], v112, off
	v_add_co_u32_e32 v110, vcc, s28, v108
	v_lshl_add_u64 v[106:107], v[106:107], 0, v[136:137]
	s_nop 0
	v_addc_co_u32_e32 v111, vcc, 0, v109, vcc
	global_store_short v[110:111], v113, off
	v_add_co_u32_e32 v110, vcc, s29, v108
	v_pk_mul_f32 v[102:103], v[102:103], v[104:105] op_sel_hi:[1,0]
	s_nop 0
	v_addc_co_u32_e32 v111, vcc, 0, v109, vcc
	global_store_short_d16_hi v[110:111], v113, off
	v_add_co_u32_e32 v110, vcc, s30, v108
	v_pk_mul_f32 v[100:101], v[100:101], v[104:105] op_sel_hi:[1,0]
	s_nop 0
	v_addc_co_u32_e32 v111, vcc, 0, v109, vcc
	v_add_co_u32_e32 v108, vcc, s7, v108
	v_pk_mul_f32 v[96:97], v[96:97], v[104:105] op_sel_hi:[1,0]
	s_nop 0
	v_addc_co_u32_e32 v109, vcc, 0, v109, vcc
	v_cvt_pk_bf16_f32 v100, v100, v101
	v_cvt_pk_bf16_f32 v101, v102, v103
	v_cvt_pk_bf16_f32 v102, v96, v97
	v_add_co_u32_e32 v96, vcc, s17, v106
	v_pk_mul_f32 v[98:99], v[98:99], v[104:105] op_sel_hi:[1,0]
	s_nop 0
	v_addc_co_u32_e32 v97, vcc, 0, v107, vcc
	global_store_short_d16_hi v[96:97], v100, off
	v_add_co_u32_e32 v96, vcc, s26, v106
	v_cvt_pk_bf16_f32 v98, v98, v99
	s_nop 0
	v_addc_co_u32_e32 v97, vcc, 0, v107, vcc
	global_store_short v[96:97], v101, off
	v_add_co_u32_e32 v96, vcc, s27, v106
	global_store_short v[106:107], v100, off
	s_nop 0
	v_addc_co_u32_e32 v97, vcc, 0, v107, vcc
	global_store_short_d16_hi v[96:97], v101, off
	v_add_co_u32_e32 v96, vcc, s28, v106
	v_add_u32_e32 v101, 0x80, v144
	s_nop 0
	v_addc_co_u32_e32 v97, vcc, 0, v107, vcc
	global_store_short v[96:97], v102, off
	v_add_co_u32_e32 v96, vcc, s29, v106
	v_cvt_pk_bf16_f32 v114, v114, v115
	s_nop 0
	v_addc_co_u32_e32 v97, vcc, 0, v107, vcc
	global_store_short_d16_hi v[96:97], v102, off
	v_add_co_u32_e32 v96, vcc, s30, v106
	global_store_short v[110:111], v114, off
	s_nop 0
	v_addc_co_u32_e32 v97, vcc, 0, v107, vcc
	global_store_short v[96:97], v98, off
	v_add_co_u32_e32 v96, vcc, s7, v106
	global_store_short_d16_hi v[108:109], v114, off
	s_nop 0
	v_addc_co_u32_e32 v97, vcc, 0, v107, vcc
	global_store_short_d16_hi v[96:97], v98, off
	v_ashrrev_i32_e32 v96, 12, v101
	v_mad_i32_i24 v98, v96, 6, s15
	v_ashrrev_i32_e32 v99, 31, v98
	v_lshlrev_b64 v[96:97], 20, v[98:99]
	v_mov_b32_e32 v99, v171
	v_or_b32_e32 v98, 1, v98
	s_nop 0
	v_fmamk_f32 v99, v99, 0x3a000000, v240
	v_cmp_gt_f32_e32 vcc, s33, v99
	v_mul_f32_e32 v100, 0x4b800000, v99
	s_nop 0
	v_cndmask_b32_e32 v99, v99, v100, vcc
	v_rsq_f32_e32 v99, v99
	s_nop 0
	v_mul_f32_e32 v100, 0x45800000, v99
	v_cndmask_b32_e32 v100, v99, v100, vcc
	v_and_b32_e32 v99, 0xfcf, v101
	v_lshlrev_b32_e32 v204, 1, v99
	v_lshl_add_u64 v[102:103], s[8:9], 0, v[204:205]
	v_lshl_add_u64 v[104:105], v[102:103], 0, v[96:97]
	v_lshl_add_u64 v[104:105], v[104:105], 0, v[136:137]
	v_pk_mul_f32 v[106:107], v[30:31], v[100:101] op_sel_hi:[1,0]
	v_pk_mul_f32 v[108:109], v[28:29], v[100:101] op_sel_hi:[1,0]
	v_pk_mul_f32 v[110:111], v[26:27], v[100:101] op_sel_hi:[1,0]
	v_pk_mul_f32 v[112:113], v[24:25], v[100:101] op_sel_hi:[1,0]
	v_cvt_pk_bf16_f32 v101, v106, v107
	v_add_co_u32_e32 v106, vcc, s17, v104
	v_cvt_pk_bf16_f32 v99, v108, v109
	s_nop 0
	v_addc_co_u32_e32 v107, vcc, 0, v105, vcc
	global_store_short_d16_hi v[106:107], v99, off
	v_add_co_u32_e32 v106, vcc, s26, v104
	v_cvt_pk_bf16_f32 v108, v112, v113
	s_nop 0
	v_addc_co_u32_e32 v107, vcc, 0, v105, vcc
	global_store_short v[106:107], v101, off
	v_add_co_u32_e32 v106, vcc, s27, v104
	global_store_short v[104:105], v99, off
	s_nop 0
	v_addc_co_u32_e32 v107, vcc, 0, v105, vcc
	global_store_short_d16_hi v[106:107], v101, off
	v_add_co_u32_e32 v106, vcc, s28, v104
	v_ashrrev_i32_e32 v99, 31, v98
	s_nop 0
	v_addc_co_u32_e32 v107, vcc, 0, v105, vcc
	global_store_short v[106:107], v108, off
	v_add_co_u32_e32 v106, vcc, s29, v104
	v_lshlrev_b64 v[98:99], 20, v[98:99]
	s_nop 0
; DI unsigned pk2(float lo, float hi) { const f32x2_t v = {lo, hi}; return __builtin_bit_cast(unsigned, __builtin_convertvector(v, bf16x2_t)); }
;     DI void operator()(const f32x4 (&acc)[2][2][4][2], const Unit& u, int wr, int wc, int fr, int fq) const {
;     ...
;                     for (int bj = 0; bj < 2; ++bj) { const int hh = (u.pn - 11) * 2 + bj;
;                         bf16_t* vp = vt + ((size_t)(bb * 6 + hh) * 128 + wc * 32 + 8 * fq) * 4096 + t;
;                         const f32x4 v0 = acc[ai][bj][m][0] * rs, v1 = acc[ai][bj][m][1] * rs;
;                         const unsigned w0 = pk2(v0[0], v0[1]), w1 = pk2(v0[2], v0[3]), w2 = pk2(v1[0], v1[1]), w3 = pk2(v1[2], v1[3]);
;                         vp[0] = (bf16_t)(w0 & 0xffffu); vp[4096] = (bf16_t)(w0 >> 16); vp[2 * 4096] = (bf16_t)(w1 & 0xffffu); vp[3 * 4096] = (bf16_t)(w1 >> 16);
;                         vp[4 * 4096] = (bf16_t)(w2 & 0xffffu); vp[5 * 4096] = (bf16_t)(w2 >> 16); vp[6 * 4096] = (bf16_t)(w3 & 0xffffu); vp[7 * 4096] = (bf16_t)(w3 >> 16); } }
	v_addc_co_u32_e32 v107, vcc, 0, v105, vcc
	global_store_short_d16_hi v[106:107], v108, off
	v_add_co_u32_e32 v106, vcc, s30, v104
	v_lshl_add_u64 v[102:103], v[102:103], 0, v[98:99]
	s_nop 0
	v_addc_co_u32_e32 v107, vcc, 0, v105, vcc
	v_add_co_u32_e32 v104, vcc, s7, v104
	v_lshl_add_u64 v[102:103], v[102:103], 0, v[136:137]
	s_nop 0
	v_addc_co_u32_e32 v105, vcc, 0, v105, vcc
	v_pk_mul_f32 v[94:95], v[94:95], v[100:101] op_sel_hi:[1,0]
	v_pk_mul_f32 v[92:93], v[92:93], v[100:101] op_sel_hi:[1,0]
	v_pk_mul_f32 v[88:89], v[88:89], v[100:101] op_sel_hi:[1,0]
	v_cvt_pk_bf16_f32 v92, v92, v93
	v_cvt_pk_bf16_f32 v93, v94, v95
	v_cvt_pk_bf16_f32 v94, v88, v89
	v_add_co_u32_e32 v88, vcc, s17, v102
	v_pk_mul_f32 v[90:91], v[90:91], v[100:101] op_sel_hi:[1,0]
	s_nop 0
	v_addc_co_u32_e32 v89, vcc, 0, v103, vcc
	global_store_short_d16_hi v[88:89], v92, off
	v_add_co_u32_e32 v88, vcc, s26, v102
	v_cvt_pk_bf16_f32 v90, v90, v91
	s_nop 0
	v_addc_co_u32_e32 v89, vcc, 0, v103, vcc
	global_store_short v[88:89], v93, off
	v_add_co_u32_e32 v88, vcc, s27, v102
	global_store_short v[102:103], v92, off
	s_nop 0
	v_addc_co_u32_e32 v89, vcc, 0, v103, vcc
	global_store_short_d16_hi v[88:89], v93, off
	v_add_co_u32_e32 v88, vcc, s28, v102
	v_cvt_pk_bf16_f32 v109, v110, v111
	s_nop 0
	v_addc_co_u32_e32 v89, vcc, 0, v103, vcc
	global_store_short v[88:89], v94, off
	v_add_co_u32_e32 v88, vcc, s29, v102
	global_store_short_d16_hi v[104:105], v109, off
	s_nop 0
	v_addc_co_u32_e32 v89, vcc, 0, v103, vcc
	global_store_short_d16_hi v[88:89], v94, off
	v_add_co_u32_e32 v88, vcc, s30, v102
	global_store_short v[106:107], v109, off
	s_nop 0
	v_addc_co_u32_e32 v89, vcc, 0, v103, vcc
	global_store_short v[88:89], v90, off
	v_add_co_u32_e32 v88, vcc, s7, v102
	s_nop 1
	v_addc_co_u32_e32 v89, vcc, 0, v103, vcc
	global_store_short_d16_hi v[88:89], v90, off
	v_mov_b32_e32 v88, v172
	v_add_u32_e32 v89, 0x90, v144
	v_and_b32_e32 v89, 0xfdf, v89
	v_lshlrev_b32_e32 v204, 1, v89
	s_nop 0
	v_fmamk_f32 v88, v88, 0x3a000000, v240
	v_cmp_gt_f32_e32 vcc, s33, v88
	v_mul_f32_e32 v90, 0x4b800000, v88
	s_nop 0
	v_cndmask_b32_e32 v88, v88, v90, vcc
	v_rsq_f32_e32 v88, v88
	s_nop 0
	v_mul_f32_e32 v90, 0x45800000, v88
	v_cndmask_b32_e32 v88, v88, v90, vcc
	v_lshl_add_u64 v[90:91], s[8:9], 0, v[204:205]
	v_lshl_add_u64 v[92:93], v[90:91], 0, v[96:97]
	v_lshl_add_u64 v[92:93], v[92:93], 0, v[136:137]
	v_pk_mul_f32 v[94:95], v[22:23], v[88:89] op_sel_hi:[1,0]
	v_pk_mul_f32 v[100:101], v[20:21], v[88:89] op_sel_hi:[1,0]
	v_pk_mul_f32 v[102:103], v[18:19], v[88:89] op_sel_hi:[1,0]
	v_pk_mul_f32 v[104:105], v[16:17], v[88:89] op_sel_hi:[1,0]
	v_cvt_pk_bf16_f32 v89, v100, v101
	v_cvt_pk_bf16_f32 v100, v94, v95
	v_add_co_u32_e32 v94, vcc, s17, v92
	v_cvt_pk_bf16_f32 v101, v104, v105
	s_nop 0
	v_addc_co_u32_e32 v95, vcc, 0, v93, vcc
	global_store_short_d16_hi v[94:95], v89, off
	v_add_co_u32_e32 v94, vcc, s26, v92
	global_store_short v[92:93], v89, off
	s_nop 0
	v_addc_co_u32_e32 v95, vcc, 0, v93, vcc
	global_store_short v[94:95], v100, off
	v_add_co_u32_e32 v94, vcc, s27, v92
	v_lshl_add_u64 v[90:91], v[90:91], 0, v[98:99]
	s_nop 0
	v_addc_co_u32_e32 v95, vcc, 0, v93, vcc
	global_store_short_d16_hi v[94:95], v100, off
	v_add_co_u32_e32 v94, vcc, s28, v92
	v_lshl_add_u64 v[90:91], v[90:91], 0, v[136:137]
	s_nop 0
	v_addc_co_u32_e32 v95, vcc, 0, v93, vcc
	global_store_short v[94:95], v101, off
	v_add_co_u32_e32 v94, vcc, s29, v92
	v_pk_mul_f32 v[86:87], v[86:87], v[88:89] op_sel_hi:[1,0]
	s_nop 0
	v_addc_co_u32_e32 v95, vcc, 0, v93, vcc
	global_store_short_d16_hi v[94:95], v101, off
	v_add_co_u32_e32 v94, vcc, s30, v92
	v_pk_mul_f32 v[84:85], v[84:85], v[88:89] op_sel_hi:[1,0]
	s_nop 0
	v_addc_co_u32_e32 v95, vcc, 0, v93, vcc
	v_add_co_u32_e32 v92, vcc, s7, v92
	v_pk_mul_f32 v[80:81], v[80:81], v[88:89] op_sel_hi:[1,0]
	s_nop 0
	v_addc_co_u32_e32 v93, vcc, 0, v93, vcc
	v_cvt_pk_bf16_f32 v84, v84, v85
	v_cvt_pk_bf16_f32 v85, v86, v87
	v_cvt_pk_bf16_f32 v86, v80, v81
	v_add_co_u32_e32 v80, vcc, s17, v90
	v_pk_mul_f32 v[82:83], v[82:83], v[88:89] op_sel_hi:[1,0]
	s_nop 0
	v_addc_co_u32_e32 v81, vcc, 0, v91, vcc
	global_store_short_d16_hi v[80:81], v84, off
	v_add_co_u32_e32 v80, vcc, s26, v90
	v_cvt_pk_bf16_f32 v82, v82, v83
	s_nop 0
	v_addc_co_u32_e32 v81, vcc, 0, v91, vcc
	global_store_short v[80:81], v85, off
	v_add_co_u32_e32 v80, vcc, s27, v90
	global_store_short v[90:91], v84, off
	s_nop 0
	v_addc_co_u32_e32 v81, vcc, 0, v91, vcc
	global_store_short_d16_hi v[80:81], v85, off
	v_add_co_u32_e32 v80, vcc, s28, v90
	v_cvt_pk_bf16_f32 v102, v102, v103
	s_nop 0
	v_addc_co_u32_e32 v81, vcc, 0, v91, vcc
	global_store_short v[80:81], v86, off
	v_add_co_u32_e32 v80, vcc, s29, v90
	global_store_short_d16_hi v[92:93], v102, off
	s_nop 0
	v_addc_co_u32_e32 v81, vcc, 0, v91, vcc
	global_store_short_d16_hi v[80:81], v86, off
	v_add_co_u32_e32 v80, vcc, s30, v90
	global_store_short v[94:95], v102, off
	s_nop 0
	v_addc_co_u32_e32 v81, vcc, 0, v91, vcc
	global_store_short v[80:81], v82, off
	v_add_co_u32_e32 v80, vcc, s7, v90
	s_nop 1
	v_addc_co_u32_e32 v81, vcc, 0, v91, vcc
	global_store_short_d16_hi v[80:81], v82, off
	v_mov_b32_e32 v80, v173
	v_add_u32_e32 v81, 0xa0, v144
	v_and_b32_e32 v81, 0xfef, v81
	v_lshlrev_b32_e32 v204, 1, v81
	s_nop 0
	v_fmamk_f32 v80, v80, 0x3a000000, v240
	v_cmp_gt_f32_e32 vcc, s33, v80
	v_mul_f32_e32 v82, 0x4b800000, v80
	s_nop 0
	v_cndmask_b32_e32 v80, v80, v82, vcc
	v_rsq_f32_e32 v80, v80
	s_nop 0
	v_mul_f32_e32 v82, 0x45800000, v80
	v_cndmask_b32_e32 v80, v80, v82, vcc
	v_lshl_add_u64 v[82:83], s[8:9], 0, v[204:205]
	v_lshl_add_u64 v[84:85], v[82:83], 0, v[96:97]
; DI unsigned pk2(float lo, float hi) { const f32x2_t v = {lo, hi}; return __builtin_bit_cast(unsigned, __builtin_convertvector(v, bf16x2_t)); }
;     DI void operator()(const f32x4 (&acc)[2][2][4][2], const Unit& u, int wr, int wc, int fr, int fq) const {
;     ...
;                     for (int bj = 0; bj < 2; ++bj) { const int hh = (u.pn - 11) * 2 + bj;
;                         bf16_t* vp = vt + ((size_t)(bb * 6 + hh) * 128 + wc * 32 + 8 * fq) * 4096 + t;
;                         const f32x4 v0 = acc[ai][bj][m][0] * rs, v1 = acc[ai][bj][m][1] * rs;
;                         const unsigned w0 = pk2(v0[0], v0[1]), w1 = pk2(v0[2], v0[3]), w2 = pk2(v1[0], v1[1]), w3 = pk2(v1[2], v1[3]);
;                         vp[0] = (bf16_t)(w0 & 0xffffu); vp[4096] = (bf16_t)(w0 >> 16); vp[2 * 4096] = (bf16_t)(w1 & 0xffffu); vp[3 * 4096] = (bf16_t)(w1 >> 16);
;                         vp[4 * 4096] = (bf16_t)(w2 & 0xffffu); vp[5 * 4096] = (bf16_t)(w2 >> 16); vp[6 * 4096] = (bf16_t)(w3 & 0xffffu); vp[7 * 4096] = (bf16_t)(w3 >> 16); } }
	v_lshl_add_u64 v[84:85], v[84:85], 0, v[136:137]
	v_pk_mul_f32 v[86:87], v[14:15], v[80:81] op_sel_hi:[1,0]
	v_pk_mul_f32 v[88:89], v[12:13], v[80:81] op_sel_hi:[1,0]
	v_pk_mul_f32 v[90:91], v[10:11], v[80:81] op_sel_hi:[1,0]
	v_pk_mul_f32 v[92:93], v[8:9], v[80:81] op_sel_hi:[1,0]
	v_cvt_pk_bf16_f32 v81, v88, v89
	v_cvt_pk_bf16_f32 v88, v86, v87
	v_add_co_u32_e32 v86, vcc, s17, v84
	v_cvt_pk_bf16_f32 v89, v92, v93
	s_nop 0
	v_addc_co_u32_e32 v87, vcc, 0, v85, vcc
	global_store_short_d16_hi v[86:87], v81, off
	v_add_co_u32_e32 v86, vcc, s26, v84
	global_store_short v[84:85], v81, off
	s_nop 0
	v_addc_co_u32_e32 v87, vcc, 0, v85, vcc
	global_store_short v[86:87], v88, off
	v_add_co_u32_e32 v86, vcc, s27, v84
	v_lshl_add_u64 v[82:83], v[82:83], 0, v[98:99]
	s_nop 0
	v_addc_co_u32_e32 v87, vcc, 0, v85, vcc
	global_store_short_d16_hi v[86:87], v88, off
	v_add_co_u32_e32 v86, vcc, s28, v84
	v_lshl_add_u64 v[82:83], v[82:83], 0, v[136:137]
	s_nop 0
	v_addc_co_u32_e32 v87, vcc, 0, v85, vcc
	global_store_short v[86:87], v89, off
	v_add_co_u32_e32 v86, vcc, s29, v84
	v_pk_mul_f32 v[78:79], v[78:79], v[80:81] op_sel_hi:[1,0]
	s_nop 0
	v_addc_co_u32_e32 v87, vcc, 0, v85, vcc
	global_store_short_d16_hi v[86:87], v89, off
	v_add_co_u32_e32 v86, vcc, s30, v84
	v_pk_mul_f32 v[76:77], v[76:77], v[80:81] op_sel_hi:[1,0]
	s_nop 0
	v_addc_co_u32_e32 v87, vcc, 0, v85, vcc
	v_add_co_u32_e32 v84, vcc, s7, v84
	v_pk_mul_f32 v[72:73], v[72:73], v[80:81] op_sel_hi:[1,0]
	s_nop 0
	v_addc_co_u32_e32 v85, vcc, 0, v85, vcc
	v_cvt_pk_bf16_f32 v76, v76, v77
	v_cvt_pk_bf16_f32 v77, v78, v79
	v_cvt_pk_bf16_f32 v78, v72, v73
	v_add_co_u32_e32 v72, vcc, s17, v82
	v_pk_mul_f32 v[74:75], v[74:75], v[80:81] op_sel_hi:[1,0]
	s_nop 0
	v_addc_co_u32_e32 v73, vcc, 0, v83, vcc
	global_store_short_d16_hi v[72:73], v76, off
	v_add_co_u32_e32 v72, vcc, s26, v82
	v_cvt_pk_bf16_f32 v74, v74, v75
	s_nop 0
	v_addc_co_u32_e32 v73, vcc, 0, v83, vcc
	global_store_short v[72:73], v77, off
	v_add_co_u32_e32 v72, vcc, s27, v82
	global_store_short v[82:83], v76, off
	s_nop 0
	v_addc_co_u32_e32 v73, vcc, 0, v83, vcc
	global_store_short_d16_hi v[72:73], v77, off
	v_add_co_u32_e32 v72, vcc, s28, v82
	v_cvt_pk_bf16_f32 v90, v90, v91
	s_nop 0
	v_addc_co_u32_e32 v73, vcc, 0, v83, vcc
	global_store_short v[72:73], v78, off
	v_add_co_u32_e32 v72, vcc, s29, v82
	global_store_short_d16_hi v[84:85], v90, off
	s_nop 0
	v_addc_co_u32_e32 v73, vcc, 0, v83, vcc
	global_store_short_d16_hi v[72:73], v78, off
	v_add_co_u32_e32 v72, vcc, s30, v82
	global_store_short v[86:87], v90, off
	s_nop 0
	v_addc_co_u32_e32 v73, vcc, 0, v83, vcc
	global_store_short v[72:73], v74, off
	v_add_co_u32_e32 v72, vcc, s7, v82
	s_nop 1
	v_addc_co_u32_e32 v73, vcc, 0, v83, vcc
	global_store_short_d16_hi v[72:73], v74, off
	v_mov_b32_e32 v73, v174
	v_add_u32_e32 v72, 0xb0, v144
	v_and_b32_e32 v72, 0xfff, v72
	v_lshlrev_b32_e32 v204, 1, v72
	s_nop 0
	v_fmamk_f32 v73, v73, 0x3a000000, v240
	v_cmp_gt_f32_e32 vcc, s33, v73
	v_mul_f32_e32 v74, 0x4b800000, v73
	s_nop 0
	v_cndmask_b32_e32 v73, v73, v74, vcc
	v_rsq_f32_e32 v73, v73
	s_nop 0
	v_mul_f32_e32 v74, 0x45800000, v73
	v_cndmask_b32_e32 v74, v73, v74, vcc
	v_lshl_add_u64 v[72:73], s[8:9], 0, v[204:205]
	v_lshl_add_u64 v[76:77], v[72:73], 0, v[96:97]
	v_lshl_add_u64 v[76:77], v[76:77], 0, v[136:137]
	v_pk_mul_f32 v[78:79], v[6:7], v[74:75] op_sel_hi:[1,0]
	v_pk_mul_f32 v[80:81], v[4:5], v[74:75] op_sel_hi:[1,0]
	v_pk_mul_f32 v[82:83], v[2:3], v[74:75] op_sel_hi:[1,0]
	v_pk_mul_f32 v[84:85], v[0:1], v[74:75] op_sel_hi:[1,0]
	v_cvt_pk_bf16_f32 v75, v80, v81
	v_cvt_pk_bf16_f32 v80, v78, v79
	v_add_co_u32_e32 v78, vcc, s17, v76
	v_cvt_pk_bf16_f32 v81, v84, v85
	s_nop 0
	v_addc_co_u32_e32 v79, vcc, 0, v77, vcc
	global_store_short_d16_hi v[78:79], v75, off
	v_add_co_u32_e32 v78, vcc, s26, v76
	global_store_short v[76:77], v75, off
	s_nop 0
	v_addc_co_u32_e32 v79, vcc, 0, v77, vcc
	global_store_short v[78:79], v80, off
	v_add_co_u32_e32 v78, vcc, s27, v76
	v_lshl_add_u64 v[72:73], v[72:73], 0, v[98:99]
	s_nop 0
	v_addc_co_u32_e32 v79, vcc, 0, v77, vcc
	global_store_short_d16_hi v[78:79], v80, off
	v_add_co_u32_e32 v78, vcc, s28, v76
	v_lshl_add_u64 v[72:73], v[72:73], 0, v[136:137]
	s_nop 0
	v_addc_co_u32_e32 v79, vcc, 0, v77, vcc
	global_store_short v[78:79], v81, off
	v_add_co_u32_e32 v78, vcc, s29, v76
	v_pk_mul_f32 v[66:67], v[66:67], v[74:75] op_sel_hi:[1,0]
	s_nop 0
	v_addc_co_u32_e32 v79, vcc, 0, v77, vcc
	global_store_short_d16_hi v[78:79], v81, off
	v_add_co_u32_e32 v78, vcc, s30, v76
	v_pk_mul_f32 v[64:65], v[64:65], v[74:75] op_sel_hi:[1,0]
	s_nop 0
	v_addc_co_u32_e32 v79, vcc, 0, v77, vcc
	v_add_co_u32_e32 v76, vcc, s7, v76
	v_pk_mul_f32 v[60:61], v[60:61], v[74:75] op_sel_hi:[1,0]
	s_nop 0
	v_addc_co_u32_e32 v77, vcc, 0, v77, vcc
	v_cvt_pk_bf16_f32 v64, v64, v65
	v_cvt_pk_bf16_f32 v65, v66, v67
	v_cvt_pk_bf16_f32 v66, v60, v61
	v_add_co_u32_e32 v60, vcc, s17, v72
	v_pk_mul_f32 v[62:63], v[62:63], v[74:75] op_sel_hi:[1,0]
	s_nop 0
	v_addc_co_u32_e32 v61, vcc, 0, v73, vcc
	global_store_short_d16_hi v[60:61], v64, off
	v_add_co_u32_e32 v60, vcc, s26, v72
	v_cvt_pk_bf16_f32 v62, v62, v63
	s_nop 0
	v_addc_co_u32_e32 v61, vcc, 0, v73, vcc
	global_store_short v[60:61], v65, off
	v_add_co_u32_e32 v60, vcc, s27, v72
	v_cvt_pk_bf16_f32 v82, v82, v83
	s_nop 0
	v_addc_co_u32_e32 v61, vcc, 0, v73, vcc
	global_store_short_d16_hi v[60:61], v65, off
	v_add_co_u32_e32 v60, vcc, 0x8000, v72
	global_store_short v[78:79], v82, off
	s_nop 0
	v_addc_co_u32_e32 v61, vcc, 0, v73, vcc
	global_store_short v[60:61], v66, off
	v_add_co_u32_e32 v60, vcc, 0xa000, v72
	global_store_short_d16_hi v[76:77], v82, off
	s_nop 0
	v_addc_co_u32_e32 v61, vcc, 0, v73, vcc
	global_store_short_d16_hi v[60:61], v66, off
	v_add_co_u32_e32 v60, vcc, 0xc000, v72
	global_store_short v[72:73], v64, off
	s_nop 0
	v_addc_co_u32_e32 v61, vcc, 0, v73, vcc
	global_store_short v[60:61], v62, off
	v_add_co_u32_e32 v60, vcc, 0xe000, v72
	s_nop 1
	v_addc_co_u32_e32 v61, vcc, 0, v73, vcc
	global_store_short_d16_hi v[60:61], v62, off
